# K-loop: all setprio flips removed, one static setprio 1 for waves 4-7 during GEMM phases
# baseline (speedup 1.0000x reference)
.LBB0_159:
	s_add_i32 m0, s90, 0x18000
	v_lshl_add_u64 v[2:3], v[2:3], 0, s[36:37]
	s_waitcnt vmcnt(2)
	s_barrier
	global_load_lds_dwordx4 v[2:3], off
	v_lshl_add_u64 v[2:3], v[4:5], 0, s[36:37]
	s_add_i32 m0, s90, 0x1a000
	s_add_i32 s64, s90, 0x8000
	global_load_lds_dwordx4 v[2:3], off
	v_lshl_add_u64 v[2:3], v[10:11], 0, s[36:37]
	s_mov_b32 m0, s64
	s_add_i32 s65, s90, 0xa000
	global_load_lds_dwordx4 v[2:3], off
	v_lshl_add_u64 v[2:3], v[12:13], 0, s[36:37]
	s_mov_b32 m0, s65
	v_and_b32_e32 v4, 15, v14
	global_load_lds_dwordx4 v[2:3], off
	s_add_i32 m0, s90, 0x1c000
	v_lshl_add_u64 v[2:3], v[6:7], 0, s[36:37]
	global_load_lds_dwordx4 v[2:3], off
	v_lshl_add_u64 v[2:3], v[8:9], 0, s[36:37]
	s_add_i32 m0, s90, 0x1e000
	v_lshlrev_b32_e32 v5, 2, v14
	global_load_lds_dwordx4 v[2:3], off
	v_bfe_u32 v3, v14, 4, 2
	v_lshlrev_b32_e32 v233, 4, v3
	s_and_b32 s1, s1, 3
	s_lshr_b32 s91, s38, 6
	v_lshl_or_b32 v1, s2, 6, v4
	v_lshl_or_b32 v4, v4, 6, v233
	s_lshl_b32 s2, s2, 13
	v_and_b32_e32 v5, 32, v5
	v_bitop3_b32 v6, v4, s2, v5 bitop3:0xde
	s_lshl_b32 s2, s1, 12
	s_add_i32 s68, s91, -2
	s_cmpk_lt_u32 s0, 0x100
	s_cselect_b64 s[22:23], -1, 0
	v_writelane_b32 v243, s22, 28
	v_bitop3_b32 v234, v4, s2, v5 bitop3:0xde
	s_lshl_b32 s0, s1, 6
	v_writelane_b32 v243, s23, 29
	s_lshl_b32 s2, s74, 3
	v_writelane_b32 v243, s42, 46
	s_cmp_lg_u64 s[42:43], 0
	s_cselect_b64 s[22:23], -1, 0
	v_writelane_b32 v243, s43, 47
	v_readlane_b32 s40, v248, 54
	v_readlane_b32 s41, v248, 55
	v_writelane_b32 v243, s22, 48
	s_cmp_lg_u64 s[40:41], 0
	v_lshlrev_b32_e32 v2, 3, v3
	v_writelane_b32 v243, s23, 49
	s_cselect_b64 s[22:23], -1, 0
	s_abs_i32 s52, s2
	v_cmp_eq_u32_e64 s[38:39], 0, v3
	v_cvt_f32_u32_e32 v3, s52
	v_readlane_b32 s42, v248, 56
	v_readlane_b32 s43, v248, 57
	s_and_b32 s41, s41, 0xffff
	v_rcp_iflag_f32_e32 v3, v3
	v_writelane_b32 v248, s40, 54
	v_writelane_b32 v243, s22, 50
	v_or_b32_e32 v236, s0, v2
	v_writelane_b32 v248, s41, 55
	v_mul_f32_e32 v3, 0x4f7ffffe, v3
	v_writelane_b32 v243, s23, 51
	v_writelane_b32 v248, s42, 56
	v_cvt_u32_f32_e32 v3, v3
	v_writelane_b32 v248, s43, 57
	v_readlane_b32 s40, v243, 5
	v_readlane_b32 s41, v243, 6
	v_writelane_b32 v243, s0, 52
	s_mov_b32 s0, s74
	v_writelane_b32 v243, s0, 53
	s_bfe_i32 s0, s0, 0x1001c
	v_lshl_or_b32 v237, s1, 5, v2
	v_writelane_b32 v243, s0, 38
	s_sub_i32 s0, 0, s52
	v_readfirstlane_b32 s1, v3
	v_add_u32_e32 v3, v17, v15
	s_waitcnt vmcnt(6)
	s_mul_i32 s0, s0, s1
	v_add_lshl_u32 v4, v3, v16, 1
	v_mov_b32_e32 v5, v0
	v_add_u32_e32 v3, v20, v18
	s_mul_hi_u32 s0, s1, s0
	v_lshl_add_u64 v[194:195], s[16:17], 0, v[4:5]
	v_add_lshl_u32 v4, v3, v19, 1
	s_mov_b32 s46, 0
	v_or_b32_e32 v235, 64, v233
	s_mov_b32 s45, s17
	s_lshl_b32 s22, s29, 15
	s_mov_b32 s23, s43
	s_and_b32 s21, s41, 0xffff
	s_mov_b32 s28, s2
	s_mov_b32 s59, s58
	s_mov_b32 s74, s58
	s_mov_b32 s75, s58
	s_mov_b32 s84, s58
	s_mov_b32 s85, s58
	s_add_i32 s0, s1, s0
	s_lshl_b32 s53, s29, 4
	v_lshl_add_u64 v[196:197], s[16:17], 0, v[4:5]
	v_add_u32_e32 v238, 0, v6
	v_lshlrev_b32_e32 v239, 2, v2
	s_barrier
	v_writelane_b32 v243, s0, 34
	v_readlane_b32 s0, v243, 30
	s_cmp_lg_u32 s0, 0
	s_cbranch_scc0 .Lprio_skip
	s_setprio 1
.Lprio_skip:
	v_readlane_b32 s0, v243, 34
	s_branch .LBB0_162

.LBB0_169:
	s_add_i32 s0, s34, 2
	s_add_u32 s1, s80, 0x80
	s_addc_u32 s35, s81, 0
	s_add_i32 s47, 0, 0x10000
	s_cmp_eq_u32 s68, s34
	s_cselect_b32 s35, s43, s35
	s_cselect_b32 s34, s42, s1
	s_cselect_b32 s67, s87, vcc_hi
	s_cselect_b32 s66, s86, vcc_lo
	s_add_i32 s1, 0, 0x14000
	s_waitcnt lgkmcnt(0)
	ds_read_b128 v[130:133], v206
	ds_read_b128 v[134:137], v206 offset:1024
	ds_read_b128 v[138:141], v206 offset:2048
	ds_read_b128 v[142:145], v206 offset:3072
	ds_read_b128 v[146:149], v207
	ds_read_b128 v[150:153], v207 offset:1024
	ds_read_b128 v[154:157], v207 offset:2048
	ds_read_b128 v[158:161], v207 offset:3072
	s_add_i32 m0, s90, 0xc000
	ds_read_b128 v[162:165], v238
	ds_read_b128 v[166:169], v238 offset:1024
	ds_read_b128 v[170:173], v238 offset:2048
	ds_read_b128 v[174:177], v238 offset:3072
	ds_read_b128 v[178:181], v238 offset:4096
	ds_read_b128 v[182:185], v238 offset:5120
	ds_read_b128 v[198:201], v238 offset:6144
	ds_read_b128 v[202:205], v238 offset:7168
	global_load_lds_dwordx4 v194, s[80:81]
	s_add_i32 m0, s90, 0xe000
	s_nop 0
	global_load_lds_dwordx4 v196, s[80:81]
	s_waitcnt vmcnt(8)
	s_waitcnt lgkmcnt(0)
	s_barrier
	v_mfma_f32_16x16x32_bf16 v[126:129], v[130:133], v[162:165], v[126:129]
	v_mfma_f32_16x16x32_bf16 v[122:125], v[138:141], v[162:165], v[122:125]
	v_mfma_f32_16x16x32_bf16 v[118:121], v[130:133], v[170:173], v[118:121]
	v_mfma_f32_16x16x32_bf16 v[102:105], v[138:141], v[170:173], v[102:105]
	v_mfma_f32_16x16x32_bf16 v[94:97], v[130:133], v[178:181], v[94:97]
	v_mfma_f32_16x16x32_bf16 v[90:93], v[138:141], v[178:181], v[90:93]
	v_mfma_f32_16x16x32_bf16 v[78:81], v[130:133], v[198:201], v[78:81]
	v_mfma_f32_16x16x32_bf16 v[74:77], v[138:141], v[198:201], v[74:77]
	v_mfma_f32_16x16x32_bf16 v[126:129], v[134:137], v[166:169], v[126:129]
	v_mfma_f32_16x16x32_bf16 v[122:125], v[142:145], v[166:169], v[122:125]
	v_mfma_f32_16x16x32_bf16 v[118:121], v[134:137], v[174:177], v[118:121]
	v_mfma_f32_16x16x32_bf16 v[102:105], v[142:145], v[174:177], v[102:105]
	v_mfma_f32_16x16x32_bf16 v[94:97], v[134:137], v[182:185], v[94:97]
	v_mfma_f32_16x16x32_bf16 v[90:93], v[142:145], v[182:185], v[90:93]
	v_mfma_f32_16x16x32_bf16 v[78:81], v[134:137], v[202:205], v[78:81]
	v_mfma_f32_16x16x32_bf16 v[74:77], v[142:145], v[202:205], v[74:77]
	v_mfma_f32_16x16x32_bf16 v[114:117], v[146:149], v[162:165], v[114:117]
	v_mfma_f32_16x16x32_bf16 v[110:113], v[154:157], v[162:165], v[110:113]
	v_mfma_f32_16x16x32_bf16 v[106:109], v[146:149], v[170:173], v[106:109]
	v_mfma_f32_16x16x32_bf16 v[98:101], v[154:157], v[170:173], v[98:101]
	v_mfma_f32_16x16x32_bf16 v[86:89], v[146:149], v[178:181], v[86:89]
	v_mfma_f32_16x16x32_bf16 v[82:85], v[154:157], v[178:181], v[82:85]
	v_mfma_f32_16x16x32_bf16 v[70:73], v[146:149], v[198:201], v[70:73]
	v_mfma_f32_16x16x32_bf16 v[66:69], v[154:157], v[198:201], v[66:69]
	v_mfma_f32_16x16x32_bf16 v[114:117], v[150:153], v[166:169], v[114:117]
	v_mfma_f32_16x16x32_bf16 v[110:113], v[158:161], v[166:169], v[110:113]
	v_mfma_f32_16x16x32_bf16 v[106:109], v[150:153], v[174:177], v[106:109]
	v_mfma_f32_16x16x32_bf16 v[98:101], v[158:161], v[174:177], v[98:101]
	v_mfma_f32_16x16x32_bf16 v[86:89], v[150:153], v[182:185], v[86:89]
	v_mfma_f32_16x16x32_bf16 v[82:85], v[158:161], v[182:185], v[82:85]
	v_mfma_f32_16x16x32_bf16 v[70:73], v[150:153], v[202:205], v[70:73]
	v_mfma_f32_16x16x32_bf16 v[66:69], v[158:161], v[202:205], v[66:69]
	s_barrier
	s_add_i32 s47, s47, s57
	s_mov_b32 m0, s47
	ds_read_b128 v[162:165], v238 offset:16384
	ds_read_b128 v[166:169], v238 offset:17408
	ds_read_b128 v[170:173], v238 offset:18432
	ds_read_b128 v[174:177], v238 offset:19456
	ds_read_b128 v[178:181], v238 offset:20480
	ds_read_b128 v[182:185], v238 offset:21504
	ds_read_b128 v[198:201], v238 offset:22528
	ds_read_b128 v[202:205], v238 offset:23552
	global_load_lds_dwordx4 v188, s[66:67]
	s_add_i32 m0, s47, 0x2000
	s_add_u32 s100, s66, s69
	s_addc_u32 s101, s67, 0
	s_add_i32 s1, s1, s57
	global_load_lds_dwordx4 v192, s[66:67]
	s_mov_b32 m0, s1
	s_nop 0
	global_load_lds_dwordx4 v188, s[100:101]
	s_add_i32 m0, s1, 0x2000
	s_nop 0
	global_load_lds_dwordx4 v192, s[100:101]
	s_mov_b32 m0, s90
	s_nop 0
	global_load_lds_dwordx4 v186, s[34:35]
	s_mov_b32 m0, s60
	s_nop 0
	global_load_lds_dwordx4 v190, s[34:35]
	s_waitcnt vmcnt(8)
	s_waitcnt lgkmcnt(0)
	s_barrier
	v_mfma_f32_16x16x32_bf16 v[62:65], v[130:133], v[162:165], v[62:65]
	v_mfma_f32_16x16x32_bf16 v[58:61], v[138:141], v[162:165], v[58:61]
	v_mfma_f32_16x16x32_bf16 v[46:49], v[130:133], v[170:173], v[46:49]
	v_mfma_f32_16x16x32_bf16 v[42:45], v[138:141], v[170:173], v[42:45]
	v_mfma_f32_16x16x32_bf16 v[30:33], v[130:133], v[178:181], v[30:33]
	v_mfma_f32_16x16x32_bf16 v[26:29], v[138:141], v[178:181], v[26:29]
	v_mfma_f32_16x16x32_bf16 v[14:17], v[130:133], v[198:201], v[14:17]
	v_mfma_f32_16x16x32_bf16 v[10:13], v[138:141], v[198:201], v[10:13]
	v_mfma_f32_16x16x32_bf16 v[62:65], v[134:137], v[166:169], v[62:65]
	v_mfma_f32_16x16x32_bf16 v[58:61], v[142:145], v[166:169], v[58:61]
	v_mfma_f32_16x16x32_bf16 v[46:49], v[134:137], v[174:177], v[46:49]
	v_mfma_f32_16x16x32_bf16 v[42:45], v[142:145], v[174:177], v[42:45]
	v_mfma_f32_16x16x32_bf16 v[30:33], v[134:137], v[182:185], v[30:33]
	v_mfma_f32_16x16x32_bf16 v[26:29], v[142:145], v[182:185], v[26:29]
	v_mfma_f32_16x16x32_bf16 v[14:17], v[134:137], v[202:205], v[14:17]
	v_mfma_f32_16x16x32_bf16 v[10:13], v[142:145], v[202:205], v[10:13]
	v_mfma_f32_16x16x32_bf16 v[54:57], v[146:149], v[162:165], v[54:57]
	v_mfma_f32_16x16x32_bf16 v[50:53], v[154:157], v[162:165], v[50:53]
	v_mfma_f32_16x16x32_bf16 v[38:41], v[146:149], v[170:173], v[38:41]
	v_mfma_f32_16x16x32_bf16 v[34:37], v[154:157], v[170:173], v[34:37]
	v_mfma_f32_16x16x32_bf16 v[22:25], v[146:149], v[178:181], v[22:25]
	v_mfma_f32_16x16x32_bf16 v[18:21], v[154:157], v[178:181], v[18:21]
	v_mfma_f32_16x16x32_bf16 v[6:9], v[146:149], v[198:201], v[6:9]
	v_mfma_f32_16x16x32_bf16 v[2:5], v[154:157], v[198:201], v[2:5]
	v_mfma_f32_16x16x32_bf16 v[54:57], v[150:153], v[166:169], v[54:57]
	v_mfma_f32_16x16x32_bf16 v[50:53], v[158:161], v[166:169], v[50:53]
	v_mfma_f32_16x16x32_bf16 v[38:41], v[150:153], v[174:177], v[38:41]
	v_mfma_f32_16x16x32_bf16 v[34:37], v[158:161], v[174:177], v[34:37]
	v_mfma_f32_16x16x32_bf16 v[22:25], v[150:153], v[182:185], v[22:25]
	v_mfma_f32_16x16x32_bf16 v[18:21], v[158:161], v[182:185], v[18:21]
	v_mfma_f32_16x16x32_bf16 v[6:9], v[150:153], v[202:205], v[6:9]
	v_mfma_f32_16x16x32_bf16 v[2:5], v[158:161], v[202:205], v[2:5]
	s_barrier
	s_add_i32 s1, 0, 0x18000
	s_add_i32 s47, 0, 0x1c000
	ds_read_b128 v[130:133], v208
	ds_read_b128 v[134:137], v208 offset:1024
	ds_read_b128 v[138:141], v208 offset:2048
	ds_read_b128 v[142:145], v208 offset:3072
	ds_read_b128 v[146:149], v209
	ds_read_b128 v[150:153], v209 offset:1024
	ds_read_b128 v[154:157], v209 offset:2048
	ds_read_b128 v[158:161], v209 offset:3072
	s_mov_b32 m0, s61
	ds_read_b128 v[162:165], v238 offset:32768
	ds_read_b128 v[166:169], v238 offset:33792
	ds_read_b128 v[170:173], v238 offset:34816
	ds_read_b128 v[174:177], v238 offset:35840
	ds_read_b128 v[178:181], v238 offset:36864
	ds_read_b128 v[182:185], v238 offset:37888
	ds_read_b128 v[198:201], v238 offset:38912
	ds_read_b128 v[202:205], v238 offset:39936
	global_load_lds_dwordx4 v194, s[34:35]
	s_mov_b32 m0, s71
	s_nop 0
	global_load_lds_dwordx4 v196, s[34:35]
	s_waitcnt vmcnt(8)
	s_waitcnt lgkmcnt(0)
	s_barrier
	v_mfma_f32_16x16x32_bf16 v[126:129], v[130:133], v[162:165], v[126:129]
	v_mfma_f32_16x16x32_bf16 v[122:125], v[138:141], v[162:165], v[122:125]
	v_mfma_f32_16x16x32_bf16 v[118:121], v[130:133], v[170:173], v[118:121]
	v_mfma_f32_16x16x32_bf16 v[102:105], v[138:141], v[170:173], v[102:105]
	v_mfma_f32_16x16x32_bf16 v[94:97], v[130:133], v[178:181], v[94:97]
	v_mfma_f32_16x16x32_bf16 v[90:93], v[138:141], v[178:181], v[90:93]
	v_mfma_f32_16x16x32_bf16 v[78:81], v[130:133], v[198:201], v[78:81]
	v_mfma_f32_16x16x32_bf16 v[74:77], v[138:141], v[198:201], v[74:77]
	v_mfma_f32_16x16x32_bf16 v[126:129], v[134:137], v[166:169], v[126:129]
	v_mfma_f32_16x16x32_bf16 v[122:125], v[142:145], v[166:169], v[122:125]
	v_mfma_f32_16x16x32_bf16 v[118:121], v[134:137], v[174:177], v[118:121]
	v_mfma_f32_16x16x32_bf16 v[102:105], v[142:145], v[174:177], v[102:105]
	v_mfma_f32_16x16x32_bf16 v[94:97], v[134:137], v[182:185], v[94:97]
	v_mfma_f32_16x16x32_bf16 v[90:93], v[142:145], v[182:185], v[90:93]
	v_mfma_f32_16x16x32_bf16 v[78:81], v[134:137], v[202:205], v[78:81]
	v_mfma_f32_16x16x32_bf16 v[74:77], v[142:145], v[202:205], v[74:77]
	v_mfma_f32_16x16x32_bf16 v[114:117], v[146:149], v[162:165], v[114:117]
	v_mfma_f32_16x16x32_bf16 v[110:113], v[154:157], v[162:165], v[110:113]
	v_mfma_f32_16x16x32_bf16 v[106:109], v[146:149], v[170:173], v[106:109]
	v_mfma_f32_16x16x32_bf16 v[98:101], v[154:157], v[170:173], v[98:101]
	v_mfma_f32_16x16x32_bf16 v[86:89], v[146:149], v[178:181], v[86:89]
	v_mfma_f32_16x16x32_bf16 v[82:85], v[154:157], v[178:181], v[82:85]
	v_mfma_f32_16x16x32_bf16 v[70:73], v[146:149], v[198:201], v[70:73]
	v_mfma_f32_16x16x32_bf16 v[66:69], v[154:157], v[198:201], v[66:69]
	v_mfma_f32_16x16x32_bf16 v[114:117], v[150:153], v[166:169], v[114:117]
	v_mfma_f32_16x16x32_bf16 v[110:113], v[158:161], v[166:169], v[110:113]
	v_mfma_f32_16x16x32_bf16 v[106:109], v[150:153], v[174:177], v[106:109]
	v_mfma_f32_16x16x32_bf16 v[98:101], v[158:161], v[174:177], v[98:101]
	v_mfma_f32_16x16x32_bf16 v[86:89], v[150:153], v[182:185], v[86:89]
	v_mfma_f32_16x16x32_bf16 v[82:85], v[158:161], v[182:185], v[82:85]
	v_mfma_f32_16x16x32_bf16 v[70:73], v[150:153], v[202:205], v[70:73]
	v_mfma_f32_16x16x32_bf16 v[66:69], v[158:161], v[202:205], v[66:69]
	s_barrier
	s_add_i32 s1, s1, s57
	s_add_u32 s66, s66, 0x80
	s_addc_u32 s67, s67, 0
	s_add_u32 s100, s100, 0x80
	s_addc_u32 s101, s101, 0
	s_add_u32 s34, s34, 0x80
	s_addc_u32 s35, s35, 0
	s_mov_b32 m0, s1
	ds_read_b128 v[162:165], v238 offset:49152
	ds_read_b128 v[166:169], v238 offset:50176
	ds_read_b128 v[170:173], v238 offset:51200
	ds_read_b128 v[174:177], v238 offset:52224
	ds_read_b128 v[178:181], v238 offset:53248
	ds_read_b128 v[182:185], v238 offset:54272
	ds_read_b128 v[198:201], v238 offset:55296
	ds_read_b128 v[202:205], v238 offset:56320
	global_load_lds_dwordx4 v188, s[66:67]
	s_add_i32 m0, s1, 0x2000
	s_add_i32 s1, s47, s57
	global_load_lds_dwordx4 v192, s[66:67]
	s_mov_b32 m0, s1
	s_nop 0
	global_load_lds_dwordx4 v188, s[100:101]
	s_add_i32 m0, s1, 0x2000
	s_nop 0
	global_load_lds_dwordx4 v192, s[100:101]
	s_mov_b32 m0, s64
	s_nop 0
	global_load_lds_dwordx4 v186, s[34:35]
	s_mov_b32 m0, s65
	s_nop 0
	global_load_lds_dwordx4 v190, s[34:35]
	s_waitcnt vmcnt(8)
	s_waitcnt lgkmcnt(0)
	s_barrier
	v_mfma_f32_16x16x32_bf16 v[62:65], v[130:133], v[162:165], v[62:65]
	v_mfma_f32_16x16x32_bf16 v[58:61], v[138:141], v[162:165], v[58:61]
	v_mfma_f32_16x16x32_bf16 v[46:49], v[130:133], v[170:173], v[46:49]
	v_mfma_f32_16x16x32_bf16 v[42:45], v[138:141], v[170:173], v[42:45]
	v_mfma_f32_16x16x32_bf16 v[30:33], v[130:133], v[178:181], v[30:33]
	v_mfma_f32_16x16x32_bf16 v[26:29], v[138:141], v[178:181], v[26:29]
	v_mfma_f32_16x16x32_bf16 v[14:17], v[130:133], v[198:201], v[14:17]
	v_mfma_f32_16x16x32_bf16 v[10:13], v[138:141], v[198:201], v[10:13]
	v_mfma_f32_16x16x32_bf16 v[62:65], v[134:137], v[166:169], v[62:65]
	v_mfma_f32_16x16x32_bf16 v[58:61], v[142:145], v[166:169], v[58:61]
	v_mfma_f32_16x16x32_bf16 v[46:49], v[134:137], v[174:177], v[46:49]
	v_mfma_f32_16x16x32_bf16 v[42:45], v[142:145], v[174:177], v[42:45]
	v_mfma_f32_16x16x32_bf16 v[30:33], v[134:137], v[182:185], v[30:33]
	v_mfma_f32_16x16x32_bf16 v[26:29], v[142:145], v[182:185], v[26:29]
	v_mfma_f32_16x16x32_bf16 v[14:17], v[134:137], v[202:205], v[14:17]
	v_mfma_f32_16x16x32_bf16 v[10:13], v[142:145], v[202:205], v[10:13]
	v_mfma_f32_16x16x32_bf16 v[54:57], v[146:149], v[162:165], v[54:57]
	v_mfma_f32_16x16x32_bf16 v[50:53], v[154:157], v[162:165], v[50:53]
	v_mfma_f32_16x16x32_bf16 v[38:41], v[146:149], v[170:173], v[38:41]
	v_mfma_f32_16x16x32_bf16 v[34:37], v[154:157], v[170:173], v[34:37]
	v_mfma_f32_16x16x32_bf16 v[22:25], v[146:149], v[178:181], v[22:25]
	v_mfma_f32_16x16x32_bf16 v[18:21], v[154:157], v[178:181], v[18:21]
	v_mfma_f32_16x16x32_bf16 v[6:9], v[146:149], v[198:201], v[6:9]
	v_mfma_f32_16x16x32_bf16 v[2:5], v[154:157], v[198:201], v[2:5]
	v_mfma_f32_16x16x32_bf16 v[54:57], v[150:153], v[166:169], v[54:57]
	v_mfma_f32_16x16x32_bf16 v[50:53], v[158:161], v[166:169], v[50:53]
	v_mfma_f32_16x16x32_bf16 v[38:41], v[150:153], v[174:177], v[38:41]
	v_mfma_f32_16x16x32_bf16 v[34:37], v[158:161], v[174:177], v[34:37]
	v_mfma_f32_16x16x32_bf16 v[22:25], v[150:153], v[182:185], v[22:25]
	v_mfma_f32_16x16x32_bf16 v[18:21], v[158:161], v[182:185], v[18:21]
	v_mfma_f32_16x16x32_bf16 v[6:9], v[150:153], v[202:205], v[6:9]
	v_mfma_f32_16x16x32_bf16 v[2:5], v[158:161], v[202:205], v[2:5]
	s_barrier
	s_add_u32 s80, s80, 0x100
	s_addc_u32 s81, s81, 0
	s_add_u32 vcc_lo, vcc_lo, 0x100
	s_addc_u32 vcc_hi, vcc_hi, 0
	s_cmp_ge_u32 s0, s91
	s_mov_b32 s34, s0
	s_cbranch_scc0 .LBB0_169
	v_readlane_b32 s0, v243, 28
	v_readlane_b32 s1, v243, 29
	s_and_b64 vcc, exec, s[0:1]
	s_cbranch_vccz .LBB0_174
	s_barrier
	v_lshl_add_u32 v198, s99, 8, v1
	s_cmp_lt_i32 s70, 1
	s_mov_b64 s[34:35], -1
	s_cbranch_scc0 .LBB0_175

.LBB0_227:
	s_setprio 0
	s_waitcnt vmcnt(0)
	v_readlane_b32 s84, v243, 1
	v_readlane_b32 s69, v243, 16
	v_readlane_b32 s85, v243, 2
	v_readlane_b32 s86, v243, 7
	v_readlane_b32 s87, v243, 8
	v_readlane_b32 s68, v243, 10
	v_readlane_b32 s80, v243, 11
	v_readlane_b32 s90, v243, 12
	v_readlane_b32 s91, v243, 13
	v_readlane_b32 s81, v243, 14
	v_readlane_b32 s82, v243, 15
	v_readlane_b32 s46, v243, 25
	v_readlane_b32 s74, v243, 53
	s_barrier
